# one synchronisation counter per 128-byte line: row-tile counters for the partials and for the normalised activations moved from 32- and 16-byte spacing to their own cache lines
# speedup vs baseline: 1.0150x; 1.0144x over previous
.LBB0_209:
	s_load_dwordx2 s[4:5], s[66:67], 0x100
	v_mov_b32_e32 v0, 0x20178
	ds_read_b32 v18, v0
	v_readlane_b32 s6, v255, 0
	s_nop 3
	s_lshr_b32 s6, s6, 3
	s_lshl_b32 s6, s6, 8
	s_add_u32 s6, s6, 0xe800480
	s_waitcnt lgkmcnt(0)
	s_add_u32 s4, s4, s6
	s_addc_u32 s5, s5, 0

.LBB0_336:
	s_waitcnt vmcnt(0)
	s_waitcnt lgkmcnt(0)
	s_barrier
	s_and_saveexec_b64 s[4:5], s[8:9]
	v_readlane_b32 s51, v255, 33
	v_readlane_b32 s50, v255, 11
	s_cbranch_execz .LBB0_388
	v_readlane_b32 s1, v255, 0
	s_nop 3
	s_lshr_b32 s1, s1, 3
	s_lshl_b32 s1, s1, 7
	s_add_u32 s1, s1, 0xe802400
	s_waitcnt lgkmcnt(0)
	s_add_u32 s2, s6, s1
	s_addc_u32 s3, s7, 0
	v_mov_b32_e32 v0, 1
	v_mov_b32_e32 v2, 0
	global_atomic_add v2, v0, s[2:3]
	v_mov_b32_e32 v0, 0x2017c
	v_mov_b32_e32 v2, 8
	ds_add_u32 v0, v2
	v_readlane_b32 s1, v255, 21
	s_nop 3
	s_cmp_lg_u32 s1, 1
	s_cbranch_scc1 .LBB0_388
	s_cmp_lg_u32 s51, 0
	s_cbranch_scc1 .LBB0_388
	v_readlane_b32 s1, v254, 51
	s_waitcnt vmcnt(0) expcnt(0) lgkmcnt(0)
	s_and_b32 s0, s0, 15
	v_mov_b32_e32 v0, s1
	ds_read_b32 v3, v0
	v_readlane_b32 s1, v254, 52
	s_waitcnt lgkmcnt(0)
	v_cmp_ne_u32_e32 vcc, 0, v3
	v_mov_b32_e32 v0, s1
	ds_read_b32 v2, v0
	s_cbranch_vccnz .LBB0_352
	s_add_u32 s8, s6, 0xe800200
	s_addc_u32 s9, s7, 0
	s_add_u32 s10, s6, 0xe800400
	s_addc_u32 s11, s7, 0
	s_add_u32 s14, s6, 0xe800500
	s_addc_u32 s15, s7, 0
	s_add_u32 s16, s6, 0xe800600
	s_addc_u32 s17, s7, 0
	s_add_u32 s18, s6, 0xe800700
	s_addc_u32 s19, s7, 0
	s_add_u32 s20, s6, 0xe800800
	s_addc_u32 s21, s7, 0
	s_add_u32 s22, s6, 0xe800900
	s_addc_u32 s23, s7, 0
	s_add_u32 s24, s6, 0xe800a00
	s_addc_u32 s25, s7, 0
	s_add_u32 s26, s6, 0xe800b00
	s_addc_u32 s27, s7, 0
	s_add_u32 s28, s6, 0xe800c00
	s_addc_u32 s29, s7, 0
	s_add_u32 s30, s6, 0xe800d00
	s_addc_u32 s31, s7, 0
	s_add_u32 s34, s6, 0xe800e00
	s_addc_u32 s35, s7, 0
	s_add_u32 s36, s6, 0xe800f00
	s_addc_u32 s37, s7, 0
	s_add_u32 s38, s6, 0xe801000
	s_addc_u32 s39, s7, 0
	s_add_u32 s40, s6, 0xe801100
	s_addc_u32 s41, s7, 0
	s_add_u32 s42, s6, 0xe801200
	s_addc_u32 s43, s7, 0
	s_add_u32 s46, s6, 0xe801300
	s_addc_u32 s47, s7, 0
	s_mov_b32 s1, 1
	s_branch .LBB0_340

.Lhf_poll:
	s_lshl_b32 s8, s8, 7
	s_lshl_b32 s9, s9, 7
	s_lshl_b32 s10, s10, 7
	s_add_i32 s8, s8, 0x2400
	s_add_i32 s9, s9, 0x2400
	s_add_i32 s10, s10, 0x2400
	v_mov_b32_e32 v3, s8
	v_mov_b32_e32 v4, s9
	v_mov_b32_e32 v5, s10
	v_mbcnt_lo_u32_b32 v10, -1, 0
	v_mbcnt_hi_u32_b32 v10, -1, v10
	v_and_b32_e32 v10, 31, v10
	v_lshlrev_b32_e32 v10, 8, v10
	v_add_u32_e32 v10, 0x480, v10
	s_waitcnt lgkmcnt(0)
	s_add_u32 s6, s6, 0xe800000
	s_addc_u32 s7, s7, 0

.LBB0_540:
	s_waitcnt vmcnt(0)
	s_waitcnt vmcnt(0) lgkmcnt(0)
	s_barrier
	s_and_saveexec_b64 s[4:5], s[8:9]
	v_readlane_b32 s0, v255, 0
	s_nop 3
	s_and_b32 s1, s0, 7
	s_lshl_b32 s1, s1, 5
	s_lshr_b32 s0, s0, 3
	s_add_i32 s0, s0, s1
	s_lshr_b32 s1, s0, 6
	s_lshl_b32 s1, s1, 3
	s_and_b32 s0, s0, 7
	s_add_i32 s0, s0, s1
	s_lshl_b32 s0, s0, 8
	s_add_u32 s0, s0, 0xe800480
	s_add_u32 s2, s6, s0
	s_addc_u32 s3, s7, 0
	v_mov_b32_e32 v0, 1
	v_mov_b32_e32 v2, 0
	global_atomic_add v2, v0, s[2:3]
	v_mov_b32_e32 v0, 0x20178
	v_mov_b32_e32 v2, 8
	ds_add_u32 v0, v2

.LBB0_1336:
	s_waitcnt vmcnt(0)
	s_waitcnt vmcnt(0) lgkmcnt(0)
	s_barrier
	s_and_saveexec_b64 s[4:5], s[8:9]
	v_readlane_b32 s0, v255, 0
	s_nop 3
	s_and_b32 s1, s0, 7
	s_lshl_b32 s1, s1, 5
	s_lshr_b32 s0, s0, 3
	s_add_i32 s0, s0, s1
	s_lshr_b32 s1, s0, 6
	s_lshl_b32 s1, s1, 3
	s_and_b32 s0, s0, 7
	s_add_i32 s0, s0, s1
	s_lshl_b32 s0, s0, 8
	s_add_u32 s0, s0, 0xe800480
	s_add_u32 s2, s6, s0
	s_addc_u32 s3, s7, 0
	v_mov_b32_e32 v0, 1
	v_mov_b32_e32 v2, 0
	global_atomic_add v2, v0, s[2:3]
	v_mov_b32_e32 v0, 0x20178
	v_mov_b32_e32 v2, 8
	ds_add_u32 v0, v2
	s_getpc_b64 s[98:99]

.LBB0_1388:
	v_mov_b32_e32 v0, 0
	v_mov_b32_e32 v17, 0
	v_mbcnt_lo_u32_b32 v0, -1, v0
	v_mbcnt_hi_u32_b32 v0, -1, v0
	v_add_u32_e32 v1, s86, v0
	s_nop 0
	v_readfirstlane_b32 s0, v1
	s_ashr_i32 s0, s0, 6
	s_add_i32 s0, s0, s55
	s_cmpk_gt_i32 s0, 0x7ff
	s_cbranch_scc1 .LBB0_1395
	s_load_dwordx2 s[8:9], s[66:67], 0x100
	v_mov_b32_e32 v1, 0x20178
	ds_read_b32 v2, v1
	v_readlane_b32 s10, v255, 0
	s_nop 3
	s_lshr_b32 s10, s10, 3
	s_lshl_b32 s10, s10, 8
	s_add_u32 s10, s10, 0xe800480
	s_waitcnt lgkmcnt(0)
	s_add_u32 s8, s8, s10
	s_addc_u32 s9, s9, 0
